# speedup vs baseline: 1.0168x; 1.0009x over previous
; #define SWRITE(S, b) do { *(bf16x8*)(V_lds + (b) * SHM_V + vst0) = S.vs0; *(bf16x8*)(V_lds + (b) * SHM_V + vst1) = S.vs1; int kc = sc * 2; \
;     *(bf16x8*)(K_lds + (b) * SHM_K + KSWZB(sr, kc)) = S.ks0; *(bf16x8*)(K_lds + (b) * SHM_K + KSWZB(32 + sr, kc)) = S.ks1; \
;     if constexpr (DQK == 192) *(bf16x8*)(K_lds + (b) * SHM_K + KSWZB(kr_row, 256 + kr_c * 2)) = S.ks2; } while (0)
; template <int DQK, int ldq, int ldk, int ldo> ...
;     ...
;   const unsigned voff0 = sr * ldk + sc, voff1 = (32 + sr) * ldk + sc, kroff = kr_row * 64 + kr_c;
;     ...
;   f32x16 pA0, pA1; float mnA, alA; bf16x8 pa0, pa1, pa2, pa3; const int NT = seq / KVBLK;
;   SLOAD(sa, 0); SWRITE(sa, 0);
;   SLOAD(sa, KVBLK);
;   __syncthreads();
.Lattn_prio_done:
	s_add_u32 s22, s54, 0x25bb1000
	s_addc_u32 s23, s55, 0
	s_add_u32 s26, s54, 0x2db35000
	s_addc_u32 s27, s55, 0
	s_add_u32 s94, s54, 0x25bf1000
	s_addc_u32 s95, s55, 0
	s_add_u32 s98, s54, 0x2db37000
	s_addc_u32 s99, s55, 0
	v_readlane_b32 s0, v253, 14
	s_mov_b32 s30, s0
	v_readlane_b32 s1, v253, 15
	s_branch .LBB0_483

; #define SBAR() __builtin_amdgcn_sched_barrier(0)
; #define PV_READS(D0, L0, H0, L1, H1, L2, H2, L3, H3) \
;   L0 = tr_read<v_rd_off(D0, 0, 0)>(vb); H0 = tr_read<v_rd_off(D0, 0, 1)>(vb); L1 = tr_read<v_rd_off(D0, 1, 0)>(vb); H1 = tr_read<v_rd_off(D0, 1, 1)>(vb); \
;   L2 = tr_read<v_rd_off(D0, 2, 0)>(vb); H2 = tr_read<v_rd_off(D0, 2, 1)>(vb); L3 = tr_read<v_rd_off(D0, 3, 0)>(vb); H3 = tr_read<v_rd_off(D0, 3, 1)>(vb);
; #define PV_MMAS(OD, L0, H0, L1, H1, L2, H2, L3, H3) \
;   OD = __builtin_amdgcn_mfma_f32_32x32x16_bf16(pa0, PK(L0, H0), OD, 0, 0, 0); OD = __builtin_amdgcn_mfma_f32_32x32x16_bf16(pa1, PK(L1, H1), OD, 0, 0, 0); \
;   OD = __builtin_amdgcn_mfma_f32_32x32x16_bf16(pa2, PK(L2, H2), OD, 0, 0, 0); OD = __builtin_amdgcn_mfma_f32_32x32x16_bf16(pa3, PK(L3, H3), OD, 0, 0, 0);
; __device__ __forceinline__ void pv_d0(f32x16* o, int vb, bf16x8 pa0, bf16x8 pa1, bf16x8 pa2, bf16x8 pa3) {
;   s16x4 al0, ah0, al1, ah1, al2, ah2, al3, ah3, bl0, bh0, bl1, bh1, bl2, bh2, bl3, bh3;
;   PV_READS(0, al0, ah0, al1, ah1, al2, ah2, al3, ah3)
;   PV_READS(1, bl0, bh0, bl1, bh1, bl2, bh2, bl3, bh3)
;   asm volatile("s_waitcnt lgkmcnt(8)" ::: "memory"); SBAR();
;   PV_MMAS(o[0], al0, ah0, al1, ah1, al2, ah2, al3, ah3)
;   SBAR();
;   PV_READS(2, al0, ah0, al1, ah1, al2, ah2, al3, ah3)
;   asm volatile("s_waitcnt lgkmcnt(8)" ::: "memory"); SBAR();
;   PV_MMAS(o[1], bl0, bh0, bl1, bh1, bl2, bh2, bl3, bh3)
;   SBAR();
;   PV_READS(3, bl0, bh0, bl1, bh1, bl2, bh2, bl3, bh3)
;   asm volatile("s_waitcnt lgkmcnt(8)" ::: "memory"); SBAR();
;   PV_MMAS(o[2], al0, ah0, al1, ah1, al2, ah2, al3, ah3)
;   asm volatile("s_waitcnt lgkmcnt(0)" ::: "memory"); SBAR();
;   PV_MMAS(o[3], bl0, bh0, bl1, bh1, bl2, bh2, bl3, bh3)
; }
; __device__ __forceinline__ void finishSM(f32x16& p0, f32x16& p1, float alpha, float& l_reg, bf16x8& pa0, bf16x8& pa1, bf16x8& pa2, bf16x8& pa3) {
; #pragma unroll
;   for (int r = 0; r < 16; ++r) p1[r] = __builtin_amdgcn_exp2f(p1[r]);
;   float ps = 0;
; #pragma unroll
;   for (int r = 0; r < 16; ++r) ps += p0[r];
; #pragma unroll
;   for (int r = 0; r < 16; ++r) ps += p1[r];
;   { auto rr = __builtin_amdgcn_permlane32_swap(__float_as_uint(ps), __float_as_uint(ps), false, false);
;     ps = __uint_as_float(rr[0]) + __uint_as_float(rr[1]); }
;   l_reg = l_reg * alpha + ps;
;     ...
;   PK4(p0, 0, pa0); PK4(p0, 8, pa1); PK4(p1, 0, pa2); PK4(p1, 8, pa3);
;     ...
; }
.Lsm_join_a:
	v_fmamk_f32 v3, v96, 0x3dd53b94, v2
	v_fmamk_f32 v96, v97, 0x3dd53b94, v2
	v_fmamk_f32 v97, v98, 0x3dd53b94, v2
	v_fmamk_f32 v98, v99, 0x3dd53b94, v2
	v_fmamk_f32 v99, v100, 0x3dd53b94, v2
	v_fmamk_f32 v100, v101, 0x3dd53b94, v2
	v_fmamk_f32 v101, v102, 0x3dd53b94, v2
	v_fmamk_f32 v102, v103, 0x3dd53b94, v2
	v_fmamk_f32 v103, v104, 0x3dd53b94, v2
	v_fmamk_f32 v104, v105, 0x3dd53b94, v2
	v_fmamk_f32 v105, v106, 0x3dd53b94, v2
	v_fmamk_f32 v106, v107, 0x3dd53b94, v2
	v_fmamk_f32 v107, v108, 0x3dd53b94, v2
	v_fmamk_f32 v108, v109, 0x3dd53b94, v2
	v_fmamk_f32 v109, v110, 0x3dd53b94, v2
	v_fmamk_f32 v110, v111, 0x3dd53b94, v2
	v_fmamk_f32 v80, v80, 0x3dd53b94, v2
	v_fmamk_f32 v81, v81, 0x3dd53b94, v2
	v_fmamk_f32 v82, v82, 0x3dd53b94, v2
	v_fmamk_f32 v83, v83, 0x3dd53b94, v2
	v_fmamk_f32 v84, v84, 0x3dd53b94, v2
	v_fmamk_f32 v85, v85, 0x3dd53b94, v2
	v_fmamk_f32 v86, v86, 0x3dd53b94, v2
	v_fmamk_f32 v87, v87, 0x3dd53b94, v2
	v_fmamk_f32 v88, v88, 0x3dd53b94, v2
	v_fmamk_f32 v89, v89, 0x3dd53b94, v2
	v_fmamk_f32 v90, v90, 0x3dd53b94, v2
	v_fmamk_f32 v91, v91, 0x3dd53b94, v2
	v_fmamk_f32 v92, v92, 0x3dd53b94, v2
	v_fmamk_f32 v93, v93, 0x3dd53b94, v2
	v_fmamk_f32 v94, v94, 0x3dd53b94, v2
	v_fmac_f32_e32 v2, 0x3dd53b94, v95
	v_exp_f32_e32 v95, v3
	v_exp_f32_e32 v96, v96
	v_exp_f32_e32 v97, v97
	v_exp_f32_e32 v98, v98
	v_exp_f32_e32 v99, v99
	v_exp_f32_e32 v232, v2
	v_add_f32_e32 v2, 0, v95
	v_exp_f32_e32 v100, v100
	v_add_f32_e32 v2, v96, v2
	v_exp_f32_e32 v101, v101
	v_add_f32_e32 v2, v97, v2
	v_exp_f32_e32 v102, v102
	v_add_f32_e32 v2, v98, v2
	v_exp_f32_e32 v103, v103
	v_add_f32_e32 v2, v99, v2
	v_exp_f32_e32 v104, v104
	v_add_f32_e32 v2, v100, v2
	v_exp_f32_e32 v105, v105
	v_add_f32_e32 v2, v101, v2
	v_exp_f32_e32 v106, v106
	v_add_f32_e32 v2, v102, v2
	v_exp_f32_e32 v107, v107
	v_add_f32_e32 v2, v103, v2
	v_exp_f32_e32 v108, v108
	v_add_f32_e32 v2, v104, v2
	v_exp_f32_e32 v109, v109
	v_add_f32_e32 v2, v105, v2
	v_exp_f32_e32 v110, v110
	v_add_f32_e32 v2, v106, v2
	v_exp_f32_e32 v111, v80
	v_add_f32_e32 v2, v107, v2
	v_exp_f32_e32 v217, v81
	v_add_f32_e32 v2, v108, v2
	v_exp_f32_e32 v219, v82
	v_add_f32_e32 v2, v109, v2
	v_exp_f32_e32 v220, v83
	v_add_f32_e32 v2, v110, v2
	v_exp_f32_e32 v221, v84
	v_add_f32_e32 v2, v111, v2
	v_exp_f32_e32 v222, v85
	v_add_f32_e32 v2, v217, v2
	v_exp_f32_e32 v223, v86
	v_add_f32_e32 v2, v219, v2
	v_exp_f32_e32 v224, v87
	v_add_f32_e32 v2, v220, v2
	v_exp_f32_e32 v225, v88
	v_add_f32_e32 v2, v221, v2
	v_exp_f32_e32 v226, v89
	v_add_f32_e32 v2, v222, v2
	v_exp_f32_e32 v227, v90
	v_add_f32_e32 v2, v223, v2
	v_exp_f32_e32 v228, v91
	v_add_f32_e32 v2, v224, v2
	v_exp_f32_e32 v229, v92
	v_add_f32_e32 v2, v225, v2
	v_exp_f32_e32 v230, v93
	v_add_f32_e32 v2, v226, v2
	v_exp_f32_e32 v231, v94
	v_add_f32_e32 v2, v227, v2
	v_add_f32_e32 v2, v228, v2
	v_add_f32_e32 v2, v229, v2
	v_add_f32_e32 v2, v230, v2
	v_add_f32_e32 v2, v231, v2
	v_add_f32_e32 v2, v232, v2
	v_mov_b32_e32 v3, v2
	s_nop 1
	v_permlane32_swap_b32_e32 v2, v3
	v_cvt_pk_bf16_f32 v80, v95, v96
	v_cvt_pk_bf16_f32 v81, v97, v98
	v_cvt_pk_bf16_f32 v82, v99, v100
	v_cvt_pk_bf16_f32 v83, v101, v102
	v_cvt_pk_bf16_f32 v84, v103, v104
	v_cvt_pk_bf16_f32 v85, v105, v106
	v_cvt_pk_bf16_f32 v86, v107, v108
	v_cvt_pk_bf16_f32 v87, v109, v110
	v_cvt_pk_bf16_f32 v88, v111, v217
	v_cvt_pk_bf16_f32 v89, v219, v220
	v_cvt_pk_bf16_f32 v90, v221, v222
	v_cvt_pk_bf16_f32 v91, v223, v224
	v_cvt_pk_bf16_f32 v92, v225, v226
	v_cvt_pk_bf16_f32 v93, v227, v228
	v_cvt_pk_bf16_f32 v94, v229, v230
	v_cvt_pk_bf16_f32 v95, v231, v232
	s_nop 0
	v_permlane32_swap_b32_e32 v80, v82
	v_permlane32_swap_b32_e32 v81, v83
	v_permlane32_swap_b32_e32 v84, v86
	v_permlane32_swap_b32_e32 v85, v87
	v_permlane32_swap_b32_e32 v88, v90
	v_permlane32_swap_b32_e32 v89, v91
	v_permlane32_swap_b32_e32 v92, v94
	v_permlane32_swap_b32_e32 v93, v95
	ds_read_b64_tr_b16 v[220:221], v183 offset:0x200
	ds_read_b64_tr_b16 v[222:223], v183 offset:0xa00
	ds_read_b64_tr_b16 v[224:225], v183 offset:0x1200
	ds_read_b64_tr_b16 v[226:227], v183 offset:0x1a00
	ds_read_b64_tr_b16 v[228:229], v183 offset:0x2200
	ds_read_b64_tr_b16 v[230:231], v183 offset:0x2a00
	ds_read_b64_tr_b16 v[232:233], v183 offset:0x3200
	ds_read_b64_tr_b16 v[234:235], v183 offset:0x3a00
	s_waitcnt lgkmcnt(8)
	s_nop 0
	v_mfma_f32_32x32x16_bf16 v[48:63], v[80:83], v[236:239], v[48:63]
	v_mfma_f32_32x32x16_bf16 v[48:63], v[84:87], v[240:243], v[48:63]
	v_mfma_f32_32x32x16_bf16 v[48:63], v[88:91], v[244:247], v[48:63]
	v_mfma_f32_32x32x16_bf16 v[48:63], v[92:95], v[248:251], v[48:63]
	ds_read_b64_tr_b16 v[96:97], v183 offset:0x400
	ds_read_b64_tr_b16 v[98:99], v183 offset:0xc00
	ds_read_b64_tr_b16 v[100:101], v183 offset:0x1400
	ds_read_b64_tr_b16 v[102:103], v183 offset:0x1c00
	ds_read_b64_tr_b16 v[104:105], v183 offset:0x2400
	ds_read_b64_tr_b16 v[106:107], v183 offset:0x2c00
	ds_read_b64_tr_b16 v[108:109], v183 offset:0x3400
	ds_read_b64_tr_b16 v[110:111], v183 offset:0x3c00
	s_waitcnt lgkmcnt(8)
	v_mfma_f32_32x32x16_bf16 v[32:47], v[80:83], v[220:223], v[32:47]
	v_mfma_f32_32x32x16_bf16 v[32:47], v[84:87], v[224:227], v[32:47]
	v_mfma_f32_32x32x16_bf16 v[32:47], v[88:91], v[228:231], v[32:47]
	v_mfma_f32_32x32x16_bf16 v[32:47], v[92:95], v[232:235], v[32:47]
	ds_read_b64_tr_b16 v[220:221], v183 offset:0x600
	ds_read_b64_tr_b16 v[222:223], v183 offset:0xe00
	ds_read_b64_tr_b16 v[224:225], v183 offset:0x1600
	ds_read_b64_tr_b16 v[226:227], v183 offset:0x1e00
	ds_read_b64_tr_b16 v[228:229], v183 offset:0x2600
	ds_read_b64_tr_b16 v[230:231], v183 offset:0x2e00
	ds_read_b64_tr_b16 v[232:233], v183 offset:0x3600
	ds_read_b64_tr_b16 v[234:235], v183 offset:0x3e00
	s_waitcnt lgkmcnt(8)
	v_mfma_f32_32x32x16_bf16 v[16:31], v[80:83], v[96:99], v[16:31]
	s_waitcnt lgkmcnt(0)
	v_mfma_f32_32x32x16_bf16 v[16:31], v[84:87], v[100:103], v[16:31]
	v_mfma_f32_32x32x16_bf16 v[16:31], v[88:91], v[104:107], v[16:31]
	v_mfma_f32_32x32x16_bf16 v[16:31], v[92:95], v[108:111], v[16:31]
	v_mfma_f32_32x32x16_bf16 v[64:79], v[80:83], v[220:223], v[64:79]
	s_add_i32 s59, s58, 2
	s_cmp_lt_u32 s59, s39
	s_cselect_b64 s[80:81], -1, 0
	s_cmp_ge_u32 s59, s39
	s_cselect_b64 s[64:65], -1, 0
	s_and_b64 vcc, exec, s[64:65]
	s_waitcnt vmcnt(4)
	ds_write_b128 v195, v[144:147] offset:16384
	s_waitcnt vmcnt(2)
	ds_write_b128 v196, v[148:151] offset:16384
	s_waitcnt vmcnt(2)
	ds_write_b128 v197, v[152:155] offset:57344
	s_waitcnt vmcnt(1)
	ds_write_b128 v198, v[156:159] offset:57344
	v_mfma_f32_32x32x16_bf16 v[64:79], v[84:87], v[224:227], v[64:79]
	s_waitcnt vmcnt(0)
	ds_write_b128 v199, v[160:163] offset:57344
	v_mfma_f32_32x32x16_bf16 v[64:79], v[88:91], v[228:231], v[64:79]
	v_mfma_f32_32x32x16_bf16 v[64:79], v[92:95], v[232:235], v[64:79]
	s_cbranch_vccnz .LBB0_494
; #define SWRITE(S, b) do { *(bf16x8*)(V_lds + (b) * SHM_V + vst0) = S.vs0; *(bf16x8*)(V_lds + (b) * SHM_V + vst1) = S.vs1; int kc = sc * 2; \
;     *(bf16x8*)(K_lds + (b) * SHM_K + KSWZB(sr, kc)) = S.ks0; *(bf16x8*)(K_lds + (b) * SHM_K + KSWZB(32 + sr, kc)) = S.ks1; \
;     if constexpr (DQK == 192) *(bf16x8*)(K_lds + (b) * SHM_K + KSWZB(kr_row, 256 + kr_c * 2)) = S.ks2; } while (0)
; template <int DQK, int ldq, int ldk, int ldo> ...
;     ...
;     SWRITE(sa, 1); if (j + 2 < NT) SLOAD(sa, (j + 2) * KVBLK);
	v_lshl_add_u64 v[80:81], s[22:23], 0, v[188:189]
	v_lshl_add_u64 v[82:83], s[22:23], 0, v[186:187]
	global_load_dwordx4 v[144:147], v[80:81], off offset:3328
	global_load_dwordx4 v[152:155], v[80:81], off offset:3072
	global_load_dwordx4 v[148:151], v[82:83], off offset:3328
	global_load_dwordx4 v[156:159], v[82:83], off offset:3072
	v_lshl_add_u64 v[80:81], s[26:27], 0, v[184:185]
	global_load_dwordx4 v[160:163], v[80:81], off offset:3072

; #define SWRITE(S, b) do { *(bf16x8*)(V_lds + (b) * SHM_V + vst0) = S.vs0; *(bf16x8*)(V_lds + (b) * SHM_V + vst1) = S.vs1; int kc = sc * 2; \
;     *(bf16x8*)(K_lds + (b) * SHM_K + KSWZB(sr, kc)) = S.ks0; *(bf16x8*)(K_lds + (b) * SHM_K + KSWZB(32 + sr, kc)) = S.ks1; \
;     if constexpr (DQK == 192) *(bf16x8*)(K_lds + (b) * SHM_K + KSWZB(kr_row, 256 + kr_c * 2)) = S.ks2; } while (0)
; #define COMPUTE(buf) do { SBAR(); qkt<DQK>(pA0, pA1, K_lds + (buf) * SHM_K, qr, r32, hi); \
;     partialSM(pA0, pA1, m_reg, mnA, alA, C, thr); RESC(alA); \
;     finishSM(pA0, pA1, alA, l_reg, pa0, pa1, pa2, pa3); SBAR(); \
;     pv_d0(o, vb0 + (buf) * SHM_V, pa0, pa1, pa2, pa3); } while (0)
; __device__ __forceinline__ void finishSM(f32x16& p0, f32x16& p1, float alpha, float& l_reg, bf16x8& pa0, bf16x8& pa1, bf16x8& pa2, bf16x8& pa3) {
; #pragma unroll
;   for (int r = 0; r < 16; ++r) p1[r] = __builtin_amdgcn_exp2f(p1[r]);
;   float ps = 0;
; #pragma unroll
;   for (int r = 0; r < 16; ++r) ps += p0[r];
; #pragma unroll
;   for (int r = 0; r < 16; ++r) ps += p1[r];
;   { auto rr = __builtin_amdgcn_permlane32_swap(__float_as_uint(ps), __float_as_uint(ps), false, false);
;     ps = __uint_as_float(rr[0]) + __uint_as_float(rr[1]); }
;   l_reg = l_reg * alpha + ps;
;     ...
;   PK4(p0, 0, pa0); PK4(p0, 8, pa1); PK4(p1, 0, pa2); PK4(p1, 8, pa3);
;     ...
; }
; template <int DQK, int ldq, int ldk, int ldo> ...
;     ...
;   f32x16 pA0, pA1; float mnA, alA; bf16x8 pa0, pa1, pa2, pa3; const int NT = seq / KVBLK;
;   SLOAD(sa, 0); SWRITE(sa, 0);
;   SLOAD(sa, KVBLK);
;   __syncthreads();
;   for (int j = 0; j < NT; j += 2) {
;     COMPUTE(0);
;     SWRITE(sa, 1); if (j + 2 < NT) SLOAD(sa, (j + 2) * KVBLK);
;     __syncthreads();
;     COMPUTE(1);
;     if (j + 2 < NT) { SWRITE(sa, 0); if (j + 3 < NT) SLOAD(sa, (j + 3) * KVBLK); }
.Lsm_join_b:
	v_fmamk_f32 v6, v96, 0x3dd53b94, v5
	v_fmamk_f32 v7, v97, 0x3dd53b94, v5
	v_fmamk_f32 v8, v98, 0x3dd53b94, v5
	v_fmamk_f32 v9, v99, 0x3dd53b94, v5
	v_fmamk_f32 v10, v100, 0x3dd53b94, v5
	v_fmamk_f32 v11, v101, 0x3dd53b94, v5
	v_fmamk_f32 v12, v102, 0x3dd53b94, v5
	v_fmamk_f32 v13, v103, 0x3dd53b94, v5
	v_fmamk_f32 v14, v104, 0x3dd53b94, v5
	v_fmamk_f32 v15, v105, 0x3dd53b94, v5
	v_fmamk_f32 v96, v106, 0x3dd53b94, v5
	v_fmamk_f32 v97, v107, 0x3dd53b94, v5
	v_fmamk_f32 v98, v108, 0x3dd53b94, v5
	v_fmamk_f32 v99, v109, 0x3dd53b94, v5
	v_fmamk_f32 v100, v110, 0x3dd53b94, v5
	v_fmamk_f32 v101, v111, 0x3dd53b94, v5
	v_fmamk_f32 v80, v80, 0x3dd53b94, v5
	v_fmamk_f32 v81, v81, 0x3dd53b94, v5
	v_fmamk_f32 v82, v82, 0x3dd53b94, v5
	v_fmamk_f32 v83, v83, 0x3dd53b94, v5
	v_fmamk_f32 v84, v84, 0x3dd53b94, v5
	v_fmamk_f32 v85, v85, 0x3dd53b94, v5
	v_fmamk_f32 v86, v86, 0x3dd53b94, v5
	v_fmamk_f32 v87, v87, 0x3dd53b94, v5
	v_fmamk_f32 v88, v88, 0x3dd53b94, v5
	v_fmamk_f32 v89, v89, 0x3dd53b94, v5
	v_fmamk_f32 v90, v90, 0x3dd53b94, v5
	v_fmamk_f32 v91, v91, 0x3dd53b94, v5
	v_fmamk_f32 v92, v92, 0x3dd53b94, v5
	v_fmamk_f32 v93, v93, 0x3dd53b94, v5
	v_fmamk_f32 v94, v94, 0x3dd53b94, v5
	v_fmac_f32_e32 v5, 0x3dd53b94, v95
	v_exp_f32_e32 v95, v6
	v_exp_f32_e32 v7, v7
	v_exp_f32_e32 v102, v8
	v_exp_f32_e32 v9, v9
	v_exp_f32_e32 v10, v10
	v_exp_f32_e32 v103, v5
	v_add_f32_e32 v5, 0, v95
	v_exp_f32_e32 v11, v11
	v_add_f32_e32 v5, v7, v5
	v_exp_f32_e32 v12, v12
	v_add_f32_e32 v5, v102, v5
	v_exp_f32_e32 v13, v13
	v_add_f32_e32 v5, v9, v5
	v_exp_f32_e32 v14, v14
	v_add_f32_e32 v5, v10, v5
	v_exp_f32_e32 v15, v15
	v_add_f32_e32 v5, v11, v5
	v_exp_f32_e32 v96, v96
	v_add_f32_e32 v5, v12, v5
	v_exp_f32_e32 v97, v97
	v_add_f32_e32 v5, v13, v5
	v_exp_f32_e32 v98, v98
	v_add_f32_e32 v5, v14, v5
	v_exp_f32_e32 v99, v99
	v_add_f32_e32 v5, v15, v5
	v_exp_f32_e32 v100, v100
	v_add_f32_e32 v5, v96, v5
	v_exp_f32_e32 v101, v101
	v_add_f32_e32 v5, v97, v5
	v_exp_f32_e32 v80, v80
	v_add_f32_e32 v5, v98, v5
	v_exp_f32_e32 v81, v81
	v_add_f32_e32 v5, v99, v5
	v_exp_f32_e32 v82, v82
	v_add_f32_e32 v5, v100, v5
	v_exp_f32_e32 v83, v83
	v_add_f32_e32 v5, v101, v5
	v_exp_f32_e32 v84, v84
	v_add_f32_e32 v5, v80, v5
	v_exp_f32_e32 v85, v85
	v_add_f32_e32 v5, v81, v5
	v_exp_f32_e32 v86, v86
	v_add_f32_e32 v5, v82, v5
	v_exp_f32_e32 v87, v87
	v_add_f32_e32 v5, v83, v5
	v_exp_f32_e32 v88, v88
	v_add_f32_e32 v5, v84, v5
	v_exp_f32_e32 v89, v89
	v_add_f32_e32 v5, v85, v5
	v_exp_f32_e32 v90, v90
	v_add_f32_e32 v5, v86, v5
	v_exp_f32_e32 v91, v91
	v_add_f32_e32 v5, v87, v5
	v_exp_f32_e32 v92, v92
	v_add_f32_e32 v5, v88, v5
	v_exp_f32_e32 v93, v93
	v_add_f32_e32 v5, v89, v5
	v_exp_f32_e32 v94, v94
	v_add_f32_e32 v5, v90, v5
	v_add_f32_e32 v5, v91, v5
	v_add_f32_e32 v5, v92, v5
	v_add_f32_e32 v5, v93, v5
	v_add_f32_e32 v5, v94, v5
	v_add_f32_e32 v5, v103, v5
	v_mov_b32_e32 v6, v5
	s_nop 1
	v_permlane32_swap_b32_e32 v5, v6
	v_cvt_pk_bf16_f32 v8, v95, v7
	v_cvt_pk_bf16_f32 v9, v102, v9
	v_cvt_pk_bf16_f32 v10, v10, v11
	v_cvt_pk_bf16_f32 v11, v12, v13
	v_cvt_pk_bf16_f32 v12, v14, v15
	v_cvt_pk_bf16_f32 v13, v96, v97
	v_cvt_pk_bf16_f32 v14, v98, v99
	v_cvt_pk_bf16_f32 v15, v100, v101
	v_cvt_pk_bf16_f32 v80, v80, v81
	v_cvt_pk_bf16_f32 v81, v82, v83
	v_cvt_pk_bf16_f32 v82, v84, v85
	v_cvt_pk_bf16_f32 v83, v86, v87
	v_cvt_pk_bf16_f32 v84, v88, v89
	v_cvt_pk_bf16_f32 v85, v90, v91
	v_cvt_pk_bf16_f32 v86, v92, v93
	v_cvt_pk_bf16_f32 v87, v94, v103
	s_nop 0
	v_permlane32_swap_b32_e32 v8, v10
	v_permlane32_swap_b32_e32 v9, v11
	v_permlane32_swap_b32_e32 v12, v14
	v_permlane32_swap_b32_e32 v13, v15
	v_permlane32_swap_b32_e32 v80, v82
	v_permlane32_swap_b32_e32 v81, v83
	v_permlane32_swap_b32_e32 v84, v86
	v_permlane32_swap_b32_e32 v85, v87
	ds_read_b64_tr_b16 v[104:105], v215 offset:0x200
	ds_read_b64_tr_b16 v[106:107], v215 offset:0xa00
	ds_read_b64_tr_b16 v[108:109], v215 offset:0x1200
	ds_read_b64_tr_b16 v[110:111], v215 offset:0x1a00
	ds_read_b64_tr_b16 v[218:219], v215 offset:0x2200
	ds_read_b64_tr_b16 v[220:221], v215 offset:0x2a00
	ds_read_b64_tr_b16 v[222:223], v215 offset:0x3200
	ds_read_b64_tr_b16 v[224:225], v215 offset:0x3a00
	s_waitcnt lgkmcnt(8)
	s_nop 0
	v_mfma_f32_32x32x16_bf16 v[48:63], v[8:11], v[236:239], v[48:63]
	v_mfma_f32_32x32x16_bf16 v[48:63], v[12:15], v[240:243], v[48:63]
	v_mfma_f32_32x32x16_bf16 v[48:63], v[80:83], v[244:247], v[48:63]
	v_mfma_f32_32x32x16_bf16 v[48:63], v[84:87], v[248:251], v[48:63]
	ds_read_b64_tr_b16 v[88:89], v215 offset:0x400
	ds_read_b64_tr_b16 v[90:91], v215 offset:0xc00
	ds_read_b64_tr_b16 v[92:93], v215 offset:0x1400
	ds_read_b64_tr_b16 v[94:95], v215 offset:0x1c00
	ds_read_b64_tr_b16 v[96:97], v215 offset:0x2400
	ds_read_b64_tr_b16 v[98:99], v215 offset:0x2c00
	ds_read_b64_tr_b16 v[100:101], v215 offset:0x3400
	ds_read_b64_tr_b16 v[102:103], v215 offset:0x3c00
	s_waitcnt lgkmcnt(8)
	v_mfma_f32_32x32x16_bf16 v[32:47], v[8:11], v[104:107], v[32:47]
	v_mfma_f32_32x32x16_bf16 v[32:47], v[12:15], v[108:111], v[32:47]
	v_mfma_f32_32x32x16_bf16 v[32:47], v[80:83], v[218:221], v[32:47]
	v_mfma_f32_32x32x16_bf16 v[32:47], v[84:87], v[222:225], v[32:47]
	ds_read_b64_tr_b16 v[104:105], v215 offset:0x600
	ds_read_b64_tr_b16 v[106:107], v215 offset:0xe00
	ds_read_b64_tr_b16 v[108:109], v215 offset:0x1600
	ds_read_b64_tr_b16 v[110:111], v215 offset:0x1e00
	ds_read_b64_tr_b16 v[218:219], v215 offset:0x2600
	ds_read_b64_tr_b16 v[220:221], v215 offset:0x2e00
	ds_read_b64_tr_b16 v[222:223], v215 offset:0x3600
	ds_read_b64_tr_b16 v[224:225], v215 offset:0x3e00
	s_waitcnt lgkmcnt(8)
	v_mfma_f32_32x32x16_bf16 v[16:31], v[8:11], v[88:91], v[16:31]
	s_waitcnt lgkmcnt(0)
	v_mfma_f32_32x32x16_bf16 v[16:31], v[12:15], v[92:95], v[16:31]
	v_mfma_f32_32x32x16_bf16 v[16:31], v[80:83], v[96:99], v[16:31]
	v_mfma_f32_32x32x16_bf16 v[16:31], v[84:87], v[100:103], v[16:31]
	v_mfma_f32_32x32x16_bf16 v[64:79], v[8:11], v[104:107], v[64:79]
	s_andn2_b64 vcc, exec, s[80:81]
	v_mfma_f32_32x32x16_bf16 v[64:79], v[12:15], v[108:111], v[64:79]
	v_mfma_f32_32x32x16_bf16 v[64:79], v[80:83], v[218:221], v[64:79]
	v_mfma_f32_32x32x16_bf16 v[64:79], v[84:87], v[222:225], v[64:79]
	s_cbranch_vccnz .LBB0_501
	s_add_i32 s0, s58, 3
	s_cmp_ge_u32 s0, s39
	s_waitcnt vmcnt(4)
	ds_write_b128 v195, v[144:147]
	s_waitcnt vmcnt(2)
	ds_write_b128 v196, v[148:151]
	ds_write_b128 v197, v[152:155] offset:32768
	s_waitcnt vmcnt(1)
	ds_write_b128 v197, v[156:159] offset:45056
	s_waitcnt vmcnt(0)
	ds_write_b128 v199, v[160:163] offset:32768
	s_cbranch_scc1 .LBB0_501
	v_lshl_add_u64 v[8:9], s[94:95], 0, v[188:189]
	v_lshl_add_u64 v[10:11], s[94:95], 0, v[186:187]
	global_load_dwordx4 v[144:147], v[8:9], off offset:3328
	global_load_dwordx4 v[152:155], v[8:9], off offset:3072
	global_load_dwordx4 v[148:151], v[10:11], off offset:3328
	global_load_dwordx4 v[156:159], v[10:11], off offset:3072
	v_lshl_add_u64 v[8:9], s[98:99], 0, v[184:185]
	global_load_dwordx4 v[160:163], v[8:9], off offset:3072
